# adds: all s_setprio flips removed from the FFN gate/up GEMM K-loop (timing-only change)
# speedup vs baseline: 1.0066x; 1.0016x over previous
; #define PG8_STAGE(bufoff, gbase, voff) do { _Pragma("unroll") for (int _i = 0; _i < 2; ++_i) \
;         __builtin_amdgcn_global_load_lds((const unsigned*)((const char*)(gbase) + (voff)[_i]), (LAS unsigned*)(lds + (bufoff) + ldsw + _i * 8192), 16, 0, 0); } while (0)
; #define PG8_LDA(dst, b, h) do { _Pragma("unroll") for (int m = 0; m < 4; ++m) _Pragma("unroll") for (int k = 0; k < 2; ++k) dst[m][k] = *(const LAS bf16x8*)(lds + PG8_SA(b, h) + aoff + m * 2048 + k * 1024); } while (0)
; #define PG8_LDB(dst, b, h) do { _Pragma("unroll") for (int n = 0; n < 2; ++n) _Pragma("unroll") for (int k = 0; k < 2; ++k) dst[n][k] = *(const LAS bf16x8*)(lds + PG8_SB(b, h) + boff + n * 2048 + k * 1024); } while (0)
; #define PG8_MMA(ai, bj, At, Bt) do { __builtin_amdgcn_s_setprio(1); _Pragma("unroll") for (int m = 0; m < 4; ++m) _Pragma("unroll") for (int n = 0; n < 2; ++n) _Pragma("unroll") for (int k = 0; k < 2; ++k) \
;         acc[ai][bj][m][n] = __builtin_amdgcn_mfma_f32_16x16x32_bf16(Bt[n][k], At[m][k], acc[ai][bj][m][n], 0, 0, 0); __builtin_amdgcn_s_setprio(0); } while (0)
; #define PG8_WAIT_V(n) asm volatile("s_waitcnt vmcnt(" #n ")" ::: "memory")
; #define PG8_WAIT_L(n) asm volatile("s_waitcnt lgkmcnt(" #n ")" ::: "memory")
; #define PG8_BAR __builtin_amdgcn_s_barrier()
; #define PG8_SCHED __builtin_amdgcn_sched_barrier(0)
; template <class Epi, class Sched>
; __device__ __forceinline__ void gemm_phase(LAS unsigned char* lds, const Gemm g, const Sched& S, const Epi& E) {
;     ...
;             PG8_LDB(B0, 0, 0); PG8_LDB(B1, 0, 1); PG8_SCHED; PG8_LDA(At, 0, 0); PG8_STAGE(PG8_SA(1, 1), a1 + hstepA, voffA);
;             PG8_WAIT_V(8); PG8_WAIT_L(0); PG8_BAR; PG8_MMA(0, 0, At, B0); PG8_MMA(0, 1, At, B1); PG8_BAR; PG8_SCHED;
;             PG8_LDA(At, 0, 1); PG8_STAGE(PG8_SB(0, 0), b2, voffB); PG8_STAGE(PG8_SB(0, 1), b2 + hstepB, voffB); PG8_STAGE(PG8_SA(0, 0), a2, voffA);
;             PG8_WAIT_V(8); PG8_WAIT_L(0); PG8_BAR; PG8_MMA(1, 0, At, B0); PG8_MMA(1, 1, At, B1); PG8_BAR; PG8_SCHED;
.LBB0_718:
	s_add_u32 s0, s44, 0xfffc0080
	s_addc_u32 s6, s45, -1
	s_add_i32 s26, 0, 0x10000
	s_cmp_eq_u32 s55, 12
	s_cselect_b32 s15, s23, s6
	s_cselect_b32 s14, s53, s0
	v_add_u32_e32 v153, s26, v148
	s_cselect_b32 s7, s19, s47
	s_cselect_b32 s6, s54, s46
	s_add_i32 s0, 0, 0x14000
	ds_read_b128 v[142:145], v153
	ds_read_b128 v[154:157], v153 offset:1024
	ds_read_b128 v[162:165], v153 offset:2048
	ds_read_b128 v[166:169], v153 offset:3072
	v_add_u32_e32 v153, s0, v148
	ds_read_b128 v[170:173], v153
	ds_read_b128 v[174:177], v153 offset:1024
	ds_read_b128 v[190:193], v153 offset:2048
	ds_read_b128 v[196:199], v153 offset:3072
	v_lshl_add_u64 v[158:159], s[44:45], 0, v[138:139]
	s_add_i32 m0, s49, 0xc000
	ds_read_b128 v[200:203], v152
	ds_read_b128 v[204:207], v152 offset:1024
	ds_read_b128 v[208:211], v152 offset:2048
	ds_read_b128 v[212:215], v152 offset:3072
	ds_read_b128 v[216:219], v152 offset:4096
	ds_read_b128 v[220:223], v152 offset:5120
	ds_read_b128 v[224:227], v152 offset:6144
	ds_read_b128 v[228:231], v152 offset:7168
	global_load_lds_dwordx4 v[158:159], off
	v_lshl_add_u64 v[158:159], s[44:45], 0, v[140:141]
	s_add_i32 m0, s49, 0xe000
	s_nop 0
	global_load_lds_dwordx4 v[158:159], off
	s_waitcnt vmcnt(8)
	s_waitcnt lgkmcnt(0)
	s_barrier
	s_waitcnt lgkmcnt(0)
	v_mfma_f32_16x16x32_bf16 v[128:131], v[142:145], v[200:203], v[128:131]
	v_mfma_f32_16x16x32_bf16 v[124:127], v[162:165], v[200:203], v[124:127]
	v_mfma_f32_16x16x32_bf16 v[112:115], v[142:145], v[208:211], v[112:115]
	v_mfma_f32_16x16x32_bf16 v[108:111], v[162:165], v[208:211], v[108:111]
	v_mfma_f32_16x16x32_bf16 v[96:99], v[142:145], v[216:219], v[96:99]
	v_mfma_f32_16x16x32_bf16 v[92:95], v[162:165], v[216:219], v[92:95]
	v_mfma_f32_16x16x32_bf16 v[80:83], v[142:145], v[224:227], v[80:83]
	v_mfma_f32_16x16x32_bf16 v[76:79], v[162:165], v[224:227], v[76:79]
	v_mfma_f32_16x16x32_bf16 v[128:131], v[154:157], v[204:207], v[128:131]
	v_mfma_f32_16x16x32_bf16 v[124:127], v[166:169], v[204:207], v[124:127]
	v_mfma_f32_16x16x32_bf16 v[112:115], v[154:157], v[212:215], v[112:115]
	v_mfma_f32_16x16x32_bf16 v[108:111], v[166:169], v[212:215], v[108:111]
	v_mfma_f32_16x16x32_bf16 v[96:99], v[154:157], v[220:223], v[96:99]
	v_mfma_f32_16x16x32_bf16 v[92:95], v[166:169], v[220:223], v[92:95]
	v_mfma_f32_16x16x32_bf16 v[80:83], v[154:157], v[228:231], v[80:83]
	v_mfma_f32_16x16x32_bf16 v[76:79], v[166:169], v[228:231], v[76:79]
	v_mfma_f32_16x16x32_bf16 v[120:123], v[170:173], v[200:203], v[120:123]
	v_mfma_f32_16x16x32_bf16 v[116:119], v[190:193], v[200:203], v[116:119]
	v_mfma_f32_16x16x32_bf16 v[104:107], v[170:173], v[208:211], v[104:107]
	v_mfma_f32_16x16x32_bf16 v[100:103], v[190:193], v[208:211], v[100:103]
	v_mfma_f32_16x16x32_bf16 v[88:91], v[170:173], v[216:219], v[88:91]
	v_mfma_f32_16x16x32_bf16 v[84:87], v[190:193], v[216:219], v[84:87]
	v_mfma_f32_16x16x32_bf16 v[72:75], v[170:173], v[224:227], v[72:75]
	v_mfma_f32_16x16x32_bf16 v[68:71], v[190:193], v[224:227], v[68:71]
	v_mfma_f32_16x16x32_bf16 v[120:123], v[174:177], v[204:207], v[120:123]
	v_mfma_f32_16x16x32_bf16 v[116:119], v[196:199], v[204:207], v[116:119]
	v_mfma_f32_16x16x32_bf16 v[104:107], v[174:177], v[212:215], v[104:107]
	v_mfma_f32_16x16x32_bf16 v[100:103], v[196:199], v[212:215], v[100:103]
	v_mfma_f32_16x16x32_bf16 v[88:91], v[174:177], v[220:223], v[88:91]
	v_mfma_f32_16x16x32_bf16 v[84:87], v[196:199], v[220:223], v[84:87]
	v_mfma_f32_16x16x32_bf16 v[72:75], v[174:177], v[228:231], v[72:75]
	v_mfma_f32_16x16x32_bf16 v[68:71], v[196:199], v[228:231], v[68:71]
	s_barrier
	s_add_i32 s26, s26, s20
	v_lshl_add_u64 v[158:159], s[6:7], 0, v[160:161]
	s_mov_b32 m0, s26
	ds_read_b128 v[200:203], v152 offset:16384
	ds_read_b128 v[204:207], v152 offset:17408
	ds_read_b128 v[208:211], v152 offset:18432
	ds_read_b128 v[212:215], v152 offset:19456
	ds_read_b128 v[216:219], v152 offset:20480
	ds_read_b128 v[220:223], v152 offset:21504
	ds_read_b128 v[224:227], v152 offset:22528
	ds_read_b128 v[228:231], v152 offset:23552
	global_load_lds_dwordx4 v[158:159], off
	s_add_i32 m0, s26, 0x2000
	s_add_u32 s56, s6, 0x40000
	v_lshl_add_u64 v[232:233], s[6:7], 0, v[136:137]
	s_addc_u32 s57, s7, 0
	s_add_i32 s0, s0, s20
	global_load_lds_dwordx4 v[232:233], off
	v_lshl_add_u64 v[234:235], s[56:57], 0, v[160:161]
	s_mov_b32 m0, s0
	v_lshl_add_u64 v[236:237], s[14:15], 0, v[134:135]
	global_load_lds_dwordx4 v[234:235], off
	v_lshl_add_u64 v[234:235], s[56:57], 0, v[136:137]
	s_add_i32 m0, s0, 0x2000
	s_nop 0
	global_load_lds_dwordx4 v[234:235], off
	v_lshl_add_u64 v[234:235], s[14:15], 0, v[132:133]
	s_mov_b32 m0, s49
	s_nop 0
	global_load_lds_dwordx4 v[234:235], off
	s_mov_b32 m0, s50
	s_nop 0
	global_load_lds_dwordx4 v[236:237], off
	s_waitcnt vmcnt(8)
	s_waitcnt lgkmcnt(0)
	s_barrier
; #define PG8_STAGE(bufoff, gbase, voff) do { _Pragma("unroll") for (int _i = 0; _i < 2; ++_i) \
;         __builtin_amdgcn_global_load_lds((const unsigned*)((const char*)(gbase) + (voff)[_i]), (LAS unsigned*)(lds + (bufoff) + ldsw + _i * 8192), 16, 0, 0); } while (0)
; #define PG8_LDA(dst, b, h) do { _Pragma("unroll") for (int m = 0; m < 4; ++m) _Pragma("unroll") for (int k = 0; k < 2; ++k) dst[m][k] = *(const LAS bf16x8*)(lds + PG8_SA(b, h) + aoff + m * 2048 + k * 1024); } while (0)
; #define PG8_LDB(dst, b, h) do { _Pragma("unroll") for (int n = 0; n < 2; ++n) _Pragma("unroll") for (int k = 0; k < 2; ++k) dst[n][k] = *(const LAS bf16x8*)(lds + PG8_SB(b, h) + boff + n * 2048 + k * 1024); } while (0)
; #define PG8_MMA(ai, bj, At, Bt) do { __builtin_amdgcn_s_setprio(1); _Pragma("unroll") for (int m = 0; m < 4; ++m) _Pragma("unroll") for (int n = 0; n < 2; ++n) _Pragma("unroll") for (int k = 0; k < 2; ++k) \
;         acc[ai][bj][m][n] = __builtin_amdgcn_mfma_f32_16x16x32_bf16(Bt[n][k], At[m][k], acc[ai][bj][m][n], 0, 0, 0); __builtin_amdgcn_s_setprio(0); } while (0)
; #define PG8_WAIT_V(n) asm volatile("s_waitcnt vmcnt(" #n ")" ::: "memory")
; #define PG8_WAIT_L(n) asm volatile("s_waitcnt lgkmcnt(" #n ")" ::: "memory")
; #define PG8_BAR __builtin_amdgcn_s_barrier()
; #define PG8_SCHED __builtin_amdgcn_sched_barrier(0)
; template <class Epi, class Sched>
; __device__ __forceinline__ void gemm_phase(LAS unsigned char* lds, const Gemm g, const Sched& S, const Epi& E) {
;     ...
;             PG8_WAIT_V(8); PG8_WAIT_L(0); PG8_BAR; PG8_MMA(1, 0, At, B0); PG8_MMA(1, 1, At, B1); PG8_BAR; PG8_SCHED;
;             PG8_LDB(B0, 1, 0); PG8_LDB(B1, 1, 1); PG8_SCHED; PG8_LDA(At, 1, 0); PG8_STAGE(PG8_SA(0, 1), a2 + hstepA, voffA);
;             PG8_WAIT_V(8); PG8_WAIT_L(0); PG8_BAR; PG8_MMA(0, 0, At, B0); PG8_MMA(0, 1, At, B1); PG8_BAR; PG8_SCHED;
	s_waitcnt lgkmcnt(0)
	v_mfma_f32_16x16x32_bf16 v[64:67], v[142:145], v[200:203], v[64:67]
	v_mfma_f32_16x16x32_bf16 v[60:63], v[162:165], v[200:203], v[60:63]
	v_mfma_f32_16x16x32_bf16 v[48:51], v[142:145], v[208:211], v[48:51]
	v_mfma_f32_16x16x32_bf16 v[44:47], v[162:165], v[208:211], v[44:47]
	v_mfma_f32_16x16x32_bf16 v[32:35], v[142:145], v[216:219], v[32:35]
	v_mfma_f32_16x16x32_bf16 v[28:31], v[162:165], v[216:219], v[28:31]
	v_mfma_f32_16x16x32_bf16 v[16:19], v[142:145], v[224:227], v[16:19]
	v_mfma_f32_16x16x32_bf16 v[12:15], v[162:165], v[224:227], v[12:15]
	v_mfma_f32_16x16x32_bf16 v[64:67], v[154:157], v[204:207], v[64:67]
	v_mfma_f32_16x16x32_bf16 v[60:63], v[166:169], v[204:207], v[60:63]
	v_mfma_f32_16x16x32_bf16 v[48:51], v[154:157], v[212:215], v[48:51]
	v_mfma_f32_16x16x32_bf16 v[44:47], v[166:169], v[212:215], v[44:47]
	v_mfma_f32_16x16x32_bf16 v[32:35], v[154:157], v[220:223], v[32:35]
	v_mfma_f32_16x16x32_bf16 v[28:31], v[166:169], v[220:223], v[28:31]
	v_mfma_f32_16x16x32_bf16 v[16:19], v[154:157], v[228:231], v[16:19]
	v_mfma_f32_16x16x32_bf16 v[12:15], v[166:169], v[228:231], v[12:15]
	v_mfma_f32_16x16x32_bf16 v[56:59], v[170:173], v[200:203], v[56:59]
	v_mfma_f32_16x16x32_bf16 v[52:55], v[190:193], v[200:203], v[52:55]
	v_mfma_f32_16x16x32_bf16 v[40:43], v[170:173], v[208:211], v[40:43]
	v_mfma_f32_16x16x32_bf16 v[36:39], v[190:193], v[208:211], v[36:39]
	v_mfma_f32_16x16x32_bf16 v[24:27], v[170:173], v[216:219], v[24:27]
	v_mfma_f32_16x16x32_bf16 v[20:23], v[190:193], v[216:219], v[20:23]
	v_mfma_f32_16x16x32_bf16 v[8:11], v[170:173], v[224:227], v[8:11]
	v_mfma_f32_16x16x32_bf16 v[4:7], v[190:193], v[224:227], v[4:7]
	v_mfma_f32_16x16x32_bf16 v[56:59], v[174:177], v[204:207], v[56:59]
	v_mfma_f32_16x16x32_bf16 v[52:55], v[196:199], v[204:207], v[52:55]
	v_mfma_f32_16x16x32_bf16 v[40:43], v[174:177], v[212:215], v[40:43]
	v_mfma_f32_16x16x32_bf16 v[36:39], v[196:199], v[212:215], v[36:39]
	v_mfma_f32_16x16x32_bf16 v[24:27], v[174:177], v[220:223], v[24:27]
	v_mfma_f32_16x16x32_bf16 v[20:23], v[196:199], v[220:223], v[20:23]
	v_mfma_f32_16x16x32_bf16 v[8:11], v[174:177], v[228:231], v[8:11]
	v_mfma_f32_16x16x32_bf16 v[4:7], v[196:199], v[228:231], v[4:7]
	s_barrier
	s_add_i32 s0, 0, 0x18000
	v_add_u32_e32 v153, s0, v148
	s_add_i32 s26, 0, 0x1c000
	ds_read_b128 v[142:145], v153
	ds_read_b128 v[154:157], v153 offset:1024
	ds_read_b128 v[162:165], v153 offset:2048
	ds_read_b128 v[166:169], v153 offset:3072
	v_add_u32_e32 v153, s26, v148
	ds_read_b128 v[170:173], v153
	ds_read_b128 v[174:177], v153 offset:1024
	ds_read_b128 v[190:193], v153 offset:2048
	ds_read_b128 v[196:199], v153 offset:3072
	s_add_u32 s14, s14, 0x40000
	s_addc_u32 s15, s15, 0
	s_mov_b32 m0, s51
	v_lshl_add_u64 v[238:239], s[14:15], 0, v[132:133]
	ds_read_b128 v[200:203], v152 offset:32768
	ds_read_b128 v[204:207], v152 offset:33792
	ds_read_b128 v[208:211], v152 offset:34816
	ds_read_b128 v[212:215], v152 offset:35840
	ds_read_b128 v[216:219], v152 offset:36864
	ds_read_b128 v[220:223], v152 offset:37888
	ds_read_b128 v[224:227], v152 offset:38912
	ds_read_b128 v[228:231], v152 offset:39936
	global_load_lds_dwordx4 v[238:239], off
	v_lshl_add_u64 v[238:239], s[14:15], 0, v[134:135]
	s_mov_b32 m0, s52
	s_nop 0
	global_load_lds_dwordx4 v[238:239], off
	s_waitcnt vmcnt(8)
	s_waitcnt lgkmcnt(0)
	s_barrier
	s_waitcnt lgkmcnt(0)
	v_mfma_f32_16x16x32_bf16 v[128:131], v[142:145], v[200:203], v[128:131]
	v_mfma_f32_16x16x32_bf16 v[124:127], v[162:165], v[200:203], v[124:127]
	v_mfma_f32_16x16x32_bf16 v[112:115], v[142:145], v[208:211], v[112:115]
	v_mfma_f32_16x16x32_bf16 v[108:111], v[162:165], v[208:211], v[108:111]
	v_mfma_f32_16x16x32_bf16 v[96:99], v[142:145], v[216:219], v[96:99]
	v_mfma_f32_16x16x32_bf16 v[92:95], v[162:165], v[216:219], v[92:95]
	v_mfma_f32_16x16x32_bf16 v[80:83], v[142:145], v[224:227], v[80:83]
	v_mfma_f32_16x16x32_bf16 v[76:79], v[162:165], v[224:227], v[76:79]
	v_mfma_f32_16x16x32_bf16 v[128:131], v[154:157], v[204:207], v[128:131]
	v_mfma_f32_16x16x32_bf16 v[124:127], v[166:169], v[204:207], v[124:127]
	v_mfma_f32_16x16x32_bf16 v[112:115], v[154:157], v[212:215], v[112:115]
	v_mfma_f32_16x16x32_bf16 v[108:111], v[166:169], v[212:215], v[108:111]
	v_mfma_f32_16x16x32_bf16 v[96:99], v[154:157], v[220:223], v[96:99]
	v_mfma_f32_16x16x32_bf16 v[92:95], v[166:169], v[220:223], v[92:95]
	v_mfma_f32_16x16x32_bf16 v[80:83], v[154:157], v[228:231], v[80:83]
	v_mfma_f32_16x16x32_bf16 v[76:79], v[166:169], v[228:231], v[76:79]
	v_mfma_f32_16x16x32_bf16 v[120:123], v[170:173], v[200:203], v[120:123]
	v_mfma_f32_16x16x32_bf16 v[116:119], v[190:193], v[200:203], v[116:119]
	v_mfma_f32_16x16x32_bf16 v[104:107], v[170:173], v[208:211], v[104:107]
	v_mfma_f32_16x16x32_bf16 v[100:103], v[190:193], v[208:211], v[100:103]
	v_mfma_f32_16x16x32_bf16 v[88:91], v[170:173], v[216:219], v[88:91]
	v_mfma_f32_16x16x32_bf16 v[84:87], v[190:193], v[216:219], v[84:87]
	v_mfma_f32_16x16x32_bf16 v[72:75], v[170:173], v[224:227], v[72:75]
	v_mfma_f32_16x16x32_bf16 v[68:71], v[190:193], v[224:227], v[68:71]
	v_mfma_f32_16x16x32_bf16 v[120:123], v[174:177], v[204:207], v[120:123]
	v_mfma_f32_16x16x32_bf16 v[116:119], v[196:199], v[204:207], v[116:119]
	v_mfma_f32_16x16x32_bf16 v[104:107], v[174:177], v[212:215], v[104:107]
	v_mfma_f32_16x16x32_bf16 v[100:103], v[196:199], v[212:215], v[100:103]
	v_mfma_f32_16x16x32_bf16 v[88:91], v[174:177], v[220:223], v[88:91]
	v_mfma_f32_16x16x32_bf16 v[84:87], v[196:199], v[220:223], v[84:87]
	v_mfma_f32_16x16x32_bf16 v[72:75], v[174:177], v[228:231], v[72:75]
	v_mfma_f32_16x16x32_bf16 v[68:71], v[196:199], v[228:231], v[68:71]
	s_barrier
; #define PG8_STAGE(bufoff, gbase, voff) do { _Pragma("unroll") for (int _i = 0; _i < 2; ++_i) \
;         __builtin_amdgcn_global_load_lds((const unsigned*)((const char*)(gbase) + (voff)[_i]), (LAS unsigned*)(lds + (bufoff) + ldsw + _i * 8192), 16, 0, 0); } while (0)
; #define PG8_LDA(dst, b, h) do { _Pragma("unroll") for (int m = 0; m < 4; ++m) _Pragma("unroll") for (int k = 0; k < 2; ++k) dst[m][k] = *(const LAS bf16x8*)(lds + PG8_SA(b, h) + aoff + m * 2048 + k * 1024); } while (0)
; #define PG8_MMA(ai, bj, At, Bt) do { __builtin_amdgcn_s_setprio(1); _Pragma("unroll") for (int m = 0; m < 4; ++m) _Pragma("unroll") for (int n = 0; n < 2; ++n) _Pragma("unroll") for (int k = 0; k < 2; ++k) \
;         acc[ai][bj][m][n] = __builtin_amdgcn_mfma_f32_16x16x32_bf16(Bt[n][k], At[m][k], acc[ai][bj][m][n], 0, 0, 0); __builtin_amdgcn_s_setprio(0); } while (0)
; #define PG8_WAIT_V(n) asm volatile("s_waitcnt vmcnt(" #n ")" ::: "memory")
; #define PG8_WAIT_L(n) asm volatile("s_waitcnt lgkmcnt(" #n ")" ::: "memory")
; #define PG8_BAR __builtin_amdgcn_s_barrier()
; #define PG8_SCHED __builtin_amdgcn_sched_barrier(0)
; template <class Epi, class Sched>
; __device__ __forceinline__ void gemm_phase(LAS unsigned char* lds, const Gemm g, const Sched& S, const Epi& E) {
;     ...
;             PG8_LDA(At, 1, 1); PG8_STAGE(PG8_SB(1, 0), b3, voffB); PG8_STAGE(PG8_SB(1, 1), b3 + hstepB, voffB); PG8_STAGE(PG8_SA(1, 0), a3, voffA);
;             PG8_WAIT_V(8); PG8_WAIT_L(0); PG8_BAR; PG8_MMA(1, 0, At, B0); PG8_MMA(1, 1, At, B1); PG8_BAR; PG8_SCHED;
;         }
;         if (wr == 0) PG8_BAR;
	s_add_i32 s0, s0, s20
	v_lshl_add_u64 v[158:159], v[158:159], 0, s[30:31]
	s_mov_b32 m0, s0
	ds_read_b128 v[200:203], v152 offset:49152
	ds_read_b128 v[204:207], v152 offset:50176
	ds_read_b128 v[208:211], v152 offset:51200
	ds_read_b128 v[212:215], v152 offset:52224
	ds_read_b128 v[216:219], v152 offset:53248
	ds_read_b128 v[220:223], v152 offset:54272
	ds_read_b128 v[224:227], v152 offset:55296
	ds_read_b128 v[228:231], v152 offset:56320
	global_load_lds_dwordx4 v[158:159], off
	s_add_i32 m0, s0, 0x2000
	s_add_u32 s6, s6, 0x40080
	v_lshl_add_u64 v[158:159], v[232:233], 0, s[30:31]
	s_addc_u32 s7, s7, 0
	s_add_i32 s0, s26, s20
	global_load_lds_dwordx4 v[158:159], off
	v_lshl_add_u64 v[158:159], s[6:7], 0, v[160:161]
	s_mov_b32 m0, s0
	s_nop 0
	global_load_lds_dwordx4 v[158:159], off
	v_lshl_add_u64 v[158:159], s[6:7], 0, v[136:137]
	s_add_i32 m0, s0, 0x2000
	s_nop 0
	global_load_lds_dwordx4 v[158:159], off
	v_lshl_add_u64 v[158:159], v[234:235], 0, s[30:31]
	s_mov_b32 m0, s24
	s_nop 0
	global_load_lds_dwordx4 v[158:159], off
	v_lshl_add_u64 v[158:159], v[236:237], 0, s[30:31]
	s_mov_b32 m0, s25
	s_nop 0
	global_load_lds_dwordx4 v[158:159], off
	s_waitcnt vmcnt(8)
	s_waitcnt lgkmcnt(0)
	s_barrier
	s_waitcnt lgkmcnt(0)
	v_mfma_f32_16x16x32_bf16 v[64:67], v[142:145], v[200:203], v[64:67]
	v_mfma_f32_16x16x32_bf16 v[60:63], v[162:165], v[200:203], v[60:63]
	v_mfma_f32_16x16x32_bf16 v[48:51], v[142:145], v[208:211], v[48:51]
	v_mfma_f32_16x16x32_bf16 v[44:47], v[162:165], v[208:211], v[44:47]
	v_mfma_f32_16x16x32_bf16 v[32:35], v[142:145], v[216:219], v[32:35]
	v_mfma_f32_16x16x32_bf16 v[28:31], v[162:165], v[216:219], v[28:31]
	v_mfma_f32_16x16x32_bf16 v[16:19], v[142:145], v[224:227], v[16:19]
	v_mfma_f32_16x16x32_bf16 v[12:15], v[162:165], v[224:227], v[12:15]
	v_mfma_f32_16x16x32_bf16 v[64:67], v[154:157], v[204:207], v[64:67]
	v_mfma_f32_16x16x32_bf16 v[60:63], v[166:169], v[204:207], v[60:63]
	v_mfma_f32_16x16x32_bf16 v[48:51], v[154:157], v[212:215], v[48:51]
	v_mfma_f32_16x16x32_bf16 v[44:47], v[166:169], v[212:215], v[44:47]
	v_mfma_f32_16x16x32_bf16 v[32:35], v[154:157], v[220:223], v[32:35]
	v_mfma_f32_16x16x32_bf16 v[28:31], v[166:169], v[220:223], v[28:31]
	v_mfma_f32_16x16x32_bf16 v[16:19], v[154:157], v[228:231], v[16:19]
	v_mfma_f32_16x16x32_bf16 v[12:15], v[166:169], v[228:231], v[12:15]
	v_mfma_f32_16x16x32_bf16 v[56:59], v[170:173], v[200:203], v[56:59]
	v_mfma_f32_16x16x32_bf16 v[52:55], v[190:193], v[200:203], v[52:55]
	v_mfma_f32_16x16x32_bf16 v[40:43], v[170:173], v[208:211], v[40:43]
	v_mfma_f32_16x16x32_bf16 v[36:39], v[190:193], v[208:211], v[36:39]
	v_mfma_f32_16x16x32_bf16 v[24:27], v[170:173], v[216:219], v[24:27]
	v_mfma_f32_16x16x32_bf16 v[20:23], v[190:193], v[216:219], v[20:23]
	v_mfma_f32_16x16x32_bf16 v[8:11], v[170:173], v[224:227], v[8:11]
	v_mfma_f32_16x16x32_bf16 v[4:7], v[190:193], v[224:227], v[4:7]
	v_mfma_f32_16x16x32_bf16 v[56:59], v[174:177], v[204:207], v[56:59]
	v_mfma_f32_16x16x32_bf16 v[52:55], v[196:199], v[204:207], v[52:55]
	v_mfma_f32_16x16x32_bf16 v[40:43], v[174:177], v[212:215], v[40:43]
	v_mfma_f32_16x16x32_bf16 v[36:39], v[196:199], v[212:215], v[36:39]
	v_mfma_f32_16x16x32_bf16 v[24:27], v[174:177], v[220:223], v[24:27]
	v_mfma_f32_16x16x32_bf16 v[20:23], v[196:199], v[220:223], v[20:23]
	v_mfma_f32_16x16x32_bf16 v[8:11], v[174:177], v[228:231], v[8:11]
	v_mfma_f32_16x16x32_bf16 v[4:7], v[196:199], v[228:231], v[4:7]
	s_barrier
	s_add_i32 s55, s55, 2
	s_add_u32 s44, s44, 0x100
	s_addc_u32 s45, s45, 0
	s_add_u32 s46, s46, 0x100
	s_addc_u32 s47, s47, 0
	s_cmp_gt_u32 s55, 13
	s_cbranch_scc0 .LBB0_718
	s_and_b64 vcc, exec, s[16:17]
	s_cbranch_vccz .LBB0_721
	s_barrier
